# EP_EA GEMM epilogue (P4): the four per-column bias quads loaded once per tile into dead K-loop operand registers instead of two loads + vmcnt(0) per piece
# baseline (speedup 1.0000x reference)
.LBB0_407:
	s_lshl_b32 s30, s60, 8
	s_add_i32 s34, s30, s46
	s_lshl_b32 s30, s61, 8
	s_or_b32 s30, s30, s47
	v_mbcnt_lo_u32_b32 v144, -1, 0
	v_mbcnt_hi_u32_b32 v144, -1, v144
	s_cmp_lt_i32 s61, 4
	v_ashrrev_i32_e32 v140, 1, v144
	v_and_b32_e32 v140, -8, v140
	s_cselect_b64 vcc, -1, 0
	v_add_u32_e32 v142, s30, v140
	s_and_b64 s[30:31], vcc, exec
	s_cselect_b32 s30, s1, s51
	s_cselect_b32 s31, s0, s50
	v_mov_b32_e32 v140, s31
	v_mov_b32_e32 v141, s30
	v_ashrrev_i32_e32 v143, 31, v142
	v_lshl_add_u64 v[140:141], v[142:143], 2, v[140:141]
	global_load_dwordx4 v[226:229], v[140:141], off
	global_load_dwordx4 v[230:233], v[140:141], off offset:16
	global_load_dwordx4 v[234:237], v[140:141], off offset:512
	global_load_dwordx4 v[238:241], v[140:141], off offset:528
	v_and_or_b32 v144, v144, 15, s34
	v_ashrrev_i32_e32 v145, 31, v144
	v_lshlrev_b64 v[146:147], 12, v[144:145]
	v_cndmask_b32_e32 v153, 1.0, v152, vcc
	v_lshl_add_u64 v[162:163], s[8:9], 0, v[146:147]
	v_lshlrev_b64 v[146:147], 1, v[142:143]
	v_lshl_add_u64 v[142:143], v[162:163], 0, v[146:147]
	s_waitcnt vmcnt(0)
	v_pk_add_f32 v[126:127], v[126:127], v[228:229]
	v_pk_add_f32 v[124:125], v[124:125], v[226:227]
	v_pk_add_f32 v[122:123], v[122:123], v[232:233]
	v_pk_add_f32 v[120:121], v[120:121], v[230:231]
	v_mul_f32_e32 v125, 0xbfb8aa3b, v125
	v_mul_f32_e32 v120, 0xbfb8aa3b, v120
	v_mul_f32_e32 v121, 0xbfb8aa3b, v121
	v_mul_f32_e32 v126, 0xbfb8aa3b, v126
	v_mul_f32_e32 v122, 0xbfb8aa3b, v122
	v_mul_f32_e32 v127, 0xbfb8aa3b, v127
	v_mul_f32_e32 v123, 0xbfb8aa3b, v123
	v_mul_f32_e32 v124, 0xbfb8aa3b, v124
	v_exp_f32_e32 v120, v120
	v_exp_f32_e32 v125, v125
	v_exp_f32_e32 v121, v121
	v_exp_f32_e32 v126, v126
	v_exp_f32_e32 v122, v122
	v_exp_f32_e32 v127, v127
	v_exp_f32_e32 v123, v123
	v_exp_f32_e32 v124, v124
	v_add_f32_e32 v120, 1.0, v120
	v_add_f32_e32 v125, 1.0, v125
	v_add_f32_e32 v121, 1.0, v121
	v_add_f32_e32 v126, 1.0, v126
	v_add_f32_e32 v122, 1.0, v122
	v_add_f32_e32 v127, 1.0, v127
	v_add_f32_e32 v123, 1.0, v123
	v_add_f32_e32 v124, 1.0, v124
	v_rcp_f32_e32 v120, v120
	v_rcp_f32_e32 v125, v125
	v_rcp_f32_e32 v121, v121
	v_rcp_f32_e32 v126, v126
	v_rcp_f32_e32 v122, v122
	v_rcp_f32_e32 v127, v127
	v_rcp_f32_e32 v123, v123
	v_rcp_f32_e32 v124, v124
	v_mul_f32_e32 v145, v153, v120
	v_mul_f32_e32 v120, v153, v125
	v_mul_f32_e32 v125, v153, v121
	v_mul_f32_e32 v121, v153, v126
	v_mul_f32_e32 v126, v153, v122
	v_mul_f32_e32 v122, v153, v127
	v_mul_f32_e32 v123, v153, v123
	v_mul_f32_e32 v124, v153, v124
	v_cvt_pk_bf16_f32 v120, v124, v120
	v_cvt_pk_bf16_f32 v121, v121, v122
	v_cvt_pk_bf16_f32 v122, v145, v125
	v_cvt_pk_bf16_f32 v123, v126, v123
	global_store_dwordx4 v[142:143], v[120:123], off
	v_pk_add_f32 v[118:119], v[118:119], v[236:237]
	v_pk_add_f32 v[116:117], v[116:117], v[234:235]
	v_pk_add_f32 v[114:115], v[114:115], v[240:241]
	v_pk_add_f32 v[112:113], v[112:113], v[238:239]
	v_mul_f32_e32 v117, 0xbfb8aa3b, v117
	v_mul_f32_e32 v112, 0xbfb8aa3b, v112
	v_mul_f32_e32 v113, 0xbfb8aa3b, v113
	v_mul_f32_e32 v118, 0xbfb8aa3b, v118
	v_mul_f32_e32 v114, 0xbfb8aa3b, v114
	v_mul_f32_e32 v119, 0xbfb8aa3b, v119
	v_mul_f32_e32 v115, 0xbfb8aa3b, v115
	v_mul_f32_e32 v116, 0xbfb8aa3b, v116
	v_exp_f32_e32 v112, v112
	v_exp_f32_e32 v117, v117
	v_exp_f32_e32 v113, v113
	v_exp_f32_e32 v118, v118
	v_exp_f32_e32 v114, v114
	v_exp_f32_e32 v119, v119
	v_exp_f32_e32 v115, v115
	v_exp_f32_e32 v116, v116
	v_add_f32_e32 v112, 1.0, v112
	v_add_f32_e32 v117, 1.0, v117
	v_add_f32_e32 v113, 1.0, v113
	v_add_f32_e32 v118, 1.0, v118
	v_add_f32_e32 v114, 1.0, v114
	v_add_f32_e32 v119, 1.0, v119
	v_add_f32_e32 v115, 1.0, v115
	v_add_f32_e32 v116, 1.0, v116
	v_rcp_f32_e32 v112, v112
	v_rcp_f32_e32 v117, v117
	v_rcp_f32_e32 v113, v113
	v_rcp_f32_e32 v118, v118
	v_rcp_f32_e32 v114, v114
	v_rcp_f32_e32 v119, v119
	v_rcp_f32_e32 v115, v115
	v_rcp_f32_e32 v116, v116
	v_mul_f32_e32 v120, v153, v112
	v_mul_f32_e32 v112, v153, v117
	v_mul_f32_e32 v117, v153, v113
	v_mul_f32_e32 v113, v153, v118
	v_mul_f32_e32 v118, v153, v114
	v_mul_f32_e32 v114, v153, v119
	v_mul_f32_e32 v115, v153, v115
	v_mul_f32_e32 v116, v153, v116
	v_cvt_pk_bf16_f32 v112, v116, v112
	v_cvt_pk_bf16_f32 v113, v113, v114
	v_cvt_pk_bf16_f32 v114, v120, v117
	v_cvt_pk_bf16_f32 v115, v118, v115
	global_store_dwordx4 v[142:143], v[112:115], off offset:256
	v_or_b32_e32 v120, 16, v144
	v_ashrrev_i32_e32 v121, 31, v120
	v_lshlrev_b64 v[120:121], 12, v[120:121]
	v_lshl_add_u64 v[120:121], s[8:9], 0, v[120:121]
	v_lshl_add_u64 v[120:121], v[120:121], 0, v[146:147]
	v_pk_add_f32 v[110:111], v[110:111], v[228:229]
	v_pk_add_f32 v[108:109], v[108:109], v[226:227]
	v_pk_add_f32 v[106:107], v[106:107], v[232:233]
	v_pk_add_f32 v[104:105], v[104:105], v[230:231]
	v_mul_f32_e32 v109, 0xbfb8aa3b, v109
	v_mul_f32_e32 v104, 0xbfb8aa3b, v104
	v_mul_f32_e32 v105, 0xbfb8aa3b, v105
	v_mul_f32_e32 v110, 0xbfb8aa3b, v110
	v_mul_f32_e32 v106, 0xbfb8aa3b, v106
	v_mul_f32_e32 v111, 0xbfb8aa3b, v111
	v_mul_f32_e32 v107, 0xbfb8aa3b, v107
	v_mul_f32_e32 v108, 0xbfb8aa3b, v108
	v_exp_f32_e32 v104, v104
	v_exp_f32_e32 v109, v109
	v_exp_f32_e32 v105, v105
	v_exp_f32_e32 v110, v110
	v_exp_f32_e32 v106, v106
	v_exp_f32_e32 v111, v111
	v_exp_f32_e32 v107, v107
	v_exp_f32_e32 v108, v108
	v_add_f32_e32 v104, 1.0, v104
	v_add_f32_e32 v109, 1.0, v109
	v_add_f32_e32 v105, 1.0, v105
	v_add_f32_e32 v110, 1.0, v110
	v_add_f32_e32 v106, 1.0, v106
	v_add_f32_e32 v111, 1.0, v111
	v_add_f32_e32 v107, 1.0, v107
	v_add_f32_e32 v108, 1.0, v108
	v_rcp_f32_e32 v104, v104
	v_rcp_f32_e32 v109, v109
	v_rcp_f32_e32 v105, v105
	v_rcp_f32_e32 v110, v110
	v_rcp_f32_e32 v106, v106
	v_rcp_f32_e32 v111, v111
	v_rcp_f32_e32 v107, v107
	v_rcp_f32_e32 v108, v108
	v_mul_f32_e32 v112, v153, v104
	v_mul_f32_e32 v104, v153, v109
	v_mul_f32_e32 v109, v153, v105
	v_mul_f32_e32 v105, v153, v110
	v_mul_f32_e32 v110, v153, v106
	v_mul_f32_e32 v106, v153, v111
	v_mul_f32_e32 v107, v153, v107
	v_mul_f32_e32 v108, v153, v108
	v_cvt_pk_bf16_f32 v104, v108, v104
	v_cvt_pk_bf16_f32 v105, v105, v106
	v_cvt_pk_bf16_f32 v106, v112, v109
	v_cvt_pk_bf16_f32 v107, v110, v107
	global_store_dwordx4 v[120:121], v[104:107], off
	v_pk_add_f32 v[102:103], v[102:103], v[236:237]
	v_pk_add_f32 v[100:101], v[100:101], v[234:235]
	v_pk_add_f32 v[98:99], v[98:99], v[240:241]
	v_pk_add_f32 v[96:97], v[96:97], v[238:239]
	v_mul_f32_e32 v101, 0xbfb8aa3b, v101
	v_mul_f32_e32 v96, 0xbfb8aa3b, v96
	v_mul_f32_e32 v97, 0xbfb8aa3b, v97
	v_mul_f32_e32 v102, 0xbfb8aa3b, v102
	v_mul_f32_e32 v98, 0xbfb8aa3b, v98
	v_mul_f32_e32 v103, 0xbfb8aa3b, v103
	v_mul_f32_e32 v99, 0xbfb8aa3b, v99
	v_mul_f32_e32 v100, 0xbfb8aa3b, v100
	v_exp_f32_e32 v96, v96
	v_exp_f32_e32 v101, v101
	v_exp_f32_e32 v97, v97
	v_exp_f32_e32 v102, v102
	v_exp_f32_e32 v98, v98
	v_exp_f32_e32 v103, v103
	v_exp_f32_e32 v99, v99
	v_exp_f32_e32 v100, v100
	v_add_f32_e32 v96, 1.0, v96
	v_add_f32_e32 v101, 1.0, v101
	v_add_f32_e32 v97, 1.0, v97
	v_add_f32_e32 v102, 1.0, v102
	v_add_f32_e32 v98, 1.0, v98
	v_add_f32_e32 v103, 1.0, v103
	v_add_f32_e32 v99, 1.0, v99
	v_add_f32_e32 v100, 1.0, v100
	v_rcp_f32_e32 v96, v96
	v_rcp_f32_e32 v101, v101
	v_rcp_f32_e32 v97, v97
	v_rcp_f32_e32 v102, v102
	v_rcp_f32_e32 v98, v98
	v_rcp_f32_e32 v103, v103
	v_rcp_f32_e32 v99, v99
	v_rcp_f32_e32 v100, v100
	v_mul_f32_e32 v104, v153, v96
	v_mul_f32_e32 v96, v153, v101
	v_mul_f32_e32 v101, v153, v97
	v_mul_f32_e32 v97, v153, v102
	v_mul_f32_e32 v102, v153, v98
	v_mul_f32_e32 v98, v153, v103
	v_mul_f32_e32 v99, v153, v99
	v_mul_f32_e32 v100, v153, v100
	v_cvt_pk_bf16_f32 v96, v100, v96
	v_cvt_pk_bf16_f32 v97, v97, v98
	v_cvt_pk_bf16_f32 v98, v104, v101
	v_cvt_pk_bf16_f32 v99, v102, v99
	global_store_dwordx4 v[120:121], v[96:99], off offset:256
	v_or_b32_e32 v104, 32, v144
	v_ashrrev_i32_e32 v105, 31, v104
	v_lshlrev_b64 v[104:105], 12, v[104:105]
	v_lshl_add_u64 v[104:105], s[8:9], 0, v[104:105]
	v_lshl_add_u64 v[104:105], v[104:105], 0, v[146:147]
	v_pk_add_f32 v[94:95], v[94:95], v[228:229]
	v_pk_add_f32 v[92:93], v[92:93], v[226:227]
	v_pk_add_f32 v[90:91], v[90:91], v[232:233]
	v_pk_add_f32 v[88:89], v[88:89], v[230:231]
	v_mul_f32_e32 v93, 0xbfb8aa3b, v93
	v_mul_f32_e32 v88, 0xbfb8aa3b, v88
	v_mul_f32_e32 v89, 0xbfb8aa3b, v89
	v_mul_f32_e32 v94, 0xbfb8aa3b, v94
	v_mul_f32_e32 v90, 0xbfb8aa3b, v90
	v_mul_f32_e32 v95, 0xbfb8aa3b, v95
	v_mul_f32_e32 v91, 0xbfb8aa3b, v91
	v_mul_f32_e32 v92, 0xbfb8aa3b, v92
	v_exp_f32_e32 v88, v88
	v_exp_f32_e32 v93, v93
	v_exp_f32_e32 v89, v89
	v_exp_f32_e32 v94, v94
	v_exp_f32_e32 v90, v90
	v_exp_f32_e32 v95, v95
	v_exp_f32_e32 v91, v91
	v_exp_f32_e32 v92, v92
	v_add_f32_e32 v88, 1.0, v88
	v_add_f32_e32 v93, 1.0, v93
	v_add_f32_e32 v89, 1.0, v89
	v_add_f32_e32 v94, 1.0, v94
	v_add_f32_e32 v90, 1.0, v90
	v_add_f32_e32 v95, 1.0, v95
	v_add_f32_e32 v91, 1.0, v91
	v_add_f32_e32 v92, 1.0, v92
	v_rcp_f32_e32 v88, v88
	v_rcp_f32_e32 v93, v93
	v_rcp_f32_e32 v89, v89
	v_rcp_f32_e32 v94, v94
	v_rcp_f32_e32 v90, v90
	v_rcp_f32_e32 v95, v95
	v_rcp_f32_e32 v91, v91
	v_rcp_f32_e32 v92, v92
	v_mul_f32_e32 v96, v153, v88
	v_mul_f32_e32 v88, v153, v93
	v_mul_f32_e32 v93, v153, v89
	v_mul_f32_e32 v89, v153, v94
	v_mul_f32_e32 v94, v153, v90
	v_mul_f32_e32 v90, v153, v95
	v_mul_f32_e32 v91, v153, v91
	v_mul_f32_e32 v92, v153, v92
	v_cvt_pk_bf16_f32 v88, v92, v88
	v_cvt_pk_bf16_f32 v89, v89, v90
	v_cvt_pk_bf16_f32 v90, v96, v93
	v_cvt_pk_bf16_f32 v91, v94, v91
	global_store_dwordx4 v[104:105], v[88:91], off
	v_pk_add_f32 v[86:87], v[86:87], v[236:237]
	v_pk_add_f32 v[84:85], v[84:85], v[234:235]
	v_pk_add_f32 v[82:83], v[82:83], v[240:241]
	v_pk_add_f32 v[80:81], v[80:81], v[238:239]
	v_mul_f32_e32 v85, 0xbfb8aa3b, v85
	v_mul_f32_e32 v80, 0xbfb8aa3b, v80
	v_mul_f32_e32 v81, 0xbfb8aa3b, v81
	v_mul_f32_e32 v86, 0xbfb8aa3b, v86
	v_mul_f32_e32 v82, 0xbfb8aa3b, v82
	v_mul_f32_e32 v87, 0xbfb8aa3b, v87
	v_mul_f32_e32 v83, 0xbfb8aa3b, v83
	v_mul_f32_e32 v84, 0xbfb8aa3b, v84
	v_exp_f32_e32 v80, v80
	v_exp_f32_e32 v85, v85
	v_exp_f32_e32 v81, v81
	v_exp_f32_e32 v86, v86
	v_exp_f32_e32 v82, v82
	v_exp_f32_e32 v87, v87
	v_exp_f32_e32 v83, v83
	v_exp_f32_e32 v84, v84
	v_add_f32_e32 v80, 1.0, v80
	v_add_f32_e32 v85, 1.0, v85
	v_add_f32_e32 v81, 1.0, v81
	v_add_f32_e32 v86, 1.0, v86
	v_add_f32_e32 v82, 1.0, v82
	v_add_f32_e32 v87, 1.0, v87
	v_add_f32_e32 v83, 1.0, v83
	v_add_f32_e32 v84, 1.0, v84
	v_rcp_f32_e32 v80, v80
	v_rcp_f32_e32 v85, v85
	v_rcp_f32_e32 v81, v81
	v_rcp_f32_e32 v86, v86
	v_rcp_f32_e32 v82, v82
	v_rcp_f32_e32 v87, v87
	v_rcp_f32_e32 v83, v83
	v_rcp_f32_e32 v84, v84
	v_mul_f32_e32 v88, v153, v80
	v_mul_f32_e32 v80, v153, v85
	v_mul_f32_e32 v85, v153, v81
	v_mul_f32_e32 v81, v153, v86
	v_mul_f32_e32 v86, v153, v82
	v_mul_f32_e32 v82, v153, v87
	v_mul_f32_e32 v83, v153, v83
	v_mul_f32_e32 v84, v153, v84
	v_cvt_pk_bf16_f32 v80, v84, v80
	v_cvt_pk_bf16_f32 v81, v81, v82
	v_cvt_pk_bf16_f32 v82, v88, v85
	v_cvt_pk_bf16_f32 v83, v86, v83
	global_store_dwordx4 v[104:105], v[80:83], off offset:256
	v_or_b32_e32 v88, 48, v144
	v_ashrrev_i32_e32 v89, 31, v88
	v_lshlrev_b64 v[88:89], 12, v[88:89]
	v_lshl_add_u64 v[88:89], s[8:9], 0, v[88:89]
	v_lshl_add_u64 v[88:89], v[88:89], 0, v[146:147]
	v_pk_add_f32 v[78:79], v[78:79], v[228:229]
	v_pk_add_f32 v[76:77], v[76:77], v[226:227]
	v_pk_add_f32 v[74:75], v[74:75], v[232:233]
	v_pk_add_f32 v[72:73], v[72:73], v[230:231]
	v_mul_f32_e32 v77, 0xbfb8aa3b, v77
	v_mul_f32_e32 v72, 0xbfb8aa3b, v72
	v_mul_f32_e32 v73, 0xbfb8aa3b, v73
	v_mul_f32_e32 v78, 0xbfb8aa3b, v78
	v_mul_f32_e32 v74, 0xbfb8aa3b, v74
	v_mul_f32_e32 v79, 0xbfb8aa3b, v79
	v_mul_f32_e32 v75, 0xbfb8aa3b, v75
	v_mul_f32_e32 v76, 0xbfb8aa3b, v76
	v_exp_f32_e32 v72, v72
	v_exp_f32_e32 v77, v77
	v_exp_f32_e32 v73, v73
	v_exp_f32_e32 v78, v78
	v_exp_f32_e32 v74, v74
	v_exp_f32_e32 v79, v79
	v_exp_f32_e32 v75, v75
	v_exp_f32_e32 v76, v76
	v_add_f32_e32 v72, 1.0, v72
	v_add_f32_e32 v77, 1.0, v77
	v_add_f32_e32 v73, 1.0, v73
	v_add_f32_e32 v78, 1.0, v78
	v_add_f32_e32 v74, 1.0, v74
	v_add_f32_e32 v79, 1.0, v79
	v_add_f32_e32 v75, 1.0, v75
	v_add_f32_e32 v76, 1.0, v76
	v_rcp_f32_e32 v72, v72
	v_rcp_f32_e32 v77, v77
	v_rcp_f32_e32 v73, v73
	v_rcp_f32_e32 v78, v78
	v_rcp_f32_e32 v74, v74
	v_rcp_f32_e32 v79, v79
	v_rcp_f32_e32 v75, v75
	v_rcp_f32_e32 v76, v76
	v_mul_f32_e32 v80, v153, v72
	v_mul_f32_e32 v72, v153, v77
	v_mul_f32_e32 v77, v153, v73
	v_mul_f32_e32 v73, v153, v78
	v_mul_f32_e32 v78, v153, v74
	v_mul_f32_e32 v74, v153, v79
	v_mul_f32_e32 v75, v153, v75
	v_mul_f32_e32 v76, v153, v76
	v_cvt_pk_bf16_f32 v72, v76, v72
	v_cvt_pk_bf16_f32 v73, v73, v74
	v_cvt_pk_bf16_f32 v74, v80, v77
	v_cvt_pk_bf16_f32 v75, v78, v75
	global_store_dwordx4 v[88:89], v[72:75], off
	v_pk_add_f32 v[70:71], v[70:71], v[236:237]
	v_pk_add_f32 v[68:69], v[68:69], v[234:235]
	v_pk_add_f32 v[66:67], v[66:67], v[240:241]
	v_pk_add_f32 v[64:65], v[64:65], v[238:239]
	v_mul_f32_e32 v69, 0xbfb8aa3b, v69
	v_mul_f32_e32 v64, 0xbfb8aa3b, v64
	v_mul_f32_e32 v65, 0xbfb8aa3b, v65
	v_mul_f32_e32 v70, 0xbfb8aa3b, v70
	v_mul_f32_e32 v66, 0xbfb8aa3b, v66
	v_mul_f32_e32 v71, 0xbfb8aa3b, v71
	v_mul_f32_e32 v67, 0xbfb8aa3b, v67
	v_mul_f32_e32 v68, 0xbfb8aa3b, v68
	v_exp_f32_e32 v64, v64
	v_exp_f32_e32 v69, v69
	v_exp_f32_e32 v65, v65
	v_exp_f32_e32 v70, v70
	v_exp_f32_e32 v66, v66
	v_exp_f32_e32 v71, v71
	v_exp_f32_e32 v67, v67
	v_exp_f32_e32 v68, v68
	v_add_f32_e32 v64, 1.0, v64
	v_add_f32_e32 v69, 1.0, v69
	v_add_f32_e32 v65, 1.0, v65
	v_add_f32_e32 v70, 1.0, v70
	v_add_f32_e32 v66, 1.0, v66
	v_add_f32_e32 v71, 1.0, v71
	v_add_f32_e32 v67, 1.0, v67
	v_add_f32_e32 v68, 1.0, v68
	v_rcp_f32_e32 v64, v64
	v_rcp_f32_e32 v69, v69
	v_rcp_f32_e32 v65, v65
	v_rcp_f32_e32 v70, v70
	v_rcp_f32_e32 v66, v66
	v_rcp_f32_e32 v71, v71
	v_rcp_f32_e32 v67, v67
	v_rcp_f32_e32 v68, v68
	v_mul_f32_e32 v72, v153, v64
	v_mul_f32_e32 v64, v153, v69
	v_mul_f32_e32 v69, v153, v65
	v_mul_f32_e32 v65, v153, v70
	v_mul_f32_e32 v70, v153, v66
	v_mul_f32_e32 v66, v153, v71
	v_mul_f32_e32 v67, v153, v67
	v_mul_f32_e32 v68, v153, v68
	v_cvt_pk_bf16_f32 v64, v68, v64
	v_cvt_pk_bf16_f32 v65, v65, v66
	v_cvt_pk_bf16_f32 v66, v72, v69
	v_cvt_pk_bf16_f32 v67, v70, v67
	global_store_dwordx4 v[88:89], v[64:67], off offset:256
	v_add_co_u32_e32 v72, vcc, s54, v142
	v_pk_add_f32 v[58:59], v[58:59], v[228:229]
	v_pk_add_f32 v[56:57], v[56:57], v[226:227]
	v_pk_add_f32 v[62:63], v[62:63], v[232:233]
	v_pk_add_f32 v[60:61], v[60:61], v[230:231]
	v_mul_f32_e32 v56, 0xbfb8aa3b, v56
	v_mul_f32_e32 v57, 0xbfb8aa3b, v57
	v_mul_f32_e32 v58, 0xbfb8aa3b, v58
	v_mul_f32_e32 v59, 0xbfb8aa3b, v59
	v_mul_f32_e32 v60, 0xbfb8aa3b, v60
	v_mul_f32_e32 v61, 0xbfb8aa3b, v61
	v_mul_f32_e32 v62, 0xbfb8aa3b, v62
	v_mul_f32_e32 v63, 0xbfb8aa3b, v63
	v_exp_f32_e32 v56, v56
	v_exp_f32_e32 v57, v57
	v_exp_f32_e32 v58, v58
	v_exp_f32_e32 v59, v59
	v_exp_f32_e32 v60, v60
	v_exp_f32_e32 v61, v61
	v_exp_f32_e32 v62, v62
	v_exp_f32_e32 v63, v63
	v_add_f32_e32 v56, 1.0, v56
	v_add_f32_e32 v57, 1.0, v57
	v_add_f32_e32 v58, 1.0, v58
	v_add_f32_e32 v59, 1.0, v59
	v_add_f32_e32 v60, 1.0, v60
	v_add_f32_e32 v61, 1.0, v61
	v_add_f32_e32 v62, 1.0, v62
	v_add_f32_e32 v63, 1.0, v63
	v_rcp_f32_e32 v56, v56
	v_rcp_f32_e32 v57, v57
	v_rcp_f32_e32 v58, v58
	v_rcp_f32_e32 v59, v59
	v_rcp_f32_e32 v60, v60
	v_rcp_f32_e32 v61, v61
	v_rcp_f32_e32 v62, v62
	v_rcp_f32_e32 v63, v63
	v_addc_co_u32_e32 v73, vcc, 0, v143, vcc
	v_mul_f32_e32 v56, v153, v56
	v_mul_f32_e32 v57, v153, v57
	v_mul_f32_e32 v58, v153, v58
	v_mul_f32_e32 v59, v153, v59
	v_mul_f32_e32 v60, v153, v60
	v_mul_f32_e32 v61, v153, v61
	v_mul_f32_e32 v62, v153, v62
	v_mul_f32_e32 v63, v153, v63
	v_cvt_pk_bf16_f32 v56, v56, v57
	v_cvt_pk_bf16_f32 v57, v58, v59
	v_cvt_pk_bf16_f32 v58, v60, v61
	v_cvt_pk_bf16_f32 v59, v62, v63
	global_store_dwordx4 v[72:73], v[56:59], off
	v_lshl_add_u64 v[64:65], v[142:143], 0, s[20:21]
	v_pk_add_f32 v[54:55], v[54:55], v[236:237]
	v_pk_add_f32 v[52:53], v[52:53], v[234:235]
	v_pk_add_f32 v[50:51], v[50:51], v[240:241]
	v_pk_add_f32 v[48:49], v[48:49], v[238:239]
	v_mul_f32_e32 v53, 0xbfb8aa3b, v53
	v_mul_f32_e32 v48, 0xbfb8aa3b, v48
	v_mul_f32_e32 v49, 0xbfb8aa3b, v49
	v_mul_f32_e32 v54, 0xbfb8aa3b, v54
	v_mul_f32_e32 v50, 0xbfb8aa3b, v50
	v_mul_f32_e32 v55, 0xbfb8aa3b, v55
	v_mul_f32_e32 v51, 0xbfb8aa3b, v51
	v_mul_f32_e32 v52, 0xbfb8aa3b, v52
	v_exp_f32_e32 v48, v48
	v_exp_f32_e32 v53, v53
	v_exp_f32_e32 v49, v49
	v_exp_f32_e32 v54, v54
	v_exp_f32_e32 v50, v50
	v_exp_f32_e32 v55, v55
	v_exp_f32_e32 v51, v51
	v_exp_f32_e32 v52, v52
	v_add_f32_e32 v48, 1.0, v48
	v_add_f32_e32 v53, 1.0, v53
	v_add_f32_e32 v49, 1.0, v49
	v_add_f32_e32 v54, 1.0, v54
	v_add_f32_e32 v50, 1.0, v50
	v_add_f32_e32 v55, 1.0, v55
	v_add_f32_e32 v51, 1.0, v51
	v_add_f32_e32 v52, 1.0, v52
	v_rcp_f32_e32 v48, v48
	v_rcp_f32_e32 v53, v53
	v_rcp_f32_e32 v49, v49
	v_rcp_f32_e32 v54, v54
	v_rcp_f32_e32 v50, v50
	v_rcp_f32_e32 v55, v55
	v_rcp_f32_e32 v51, v51
	v_rcp_f32_e32 v52, v52
	v_mul_f32_e32 v56, v153, v48
	v_mul_f32_e32 v48, v153, v53
	v_mul_f32_e32 v53, v153, v49
	v_mul_f32_e32 v49, v153, v54
	v_mul_f32_e32 v54, v153, v50
	v_mul_f32_e32 v50, v153, v55
	v_mul_f32_e32 v51, v153, v51
	v_mul_f32_e32 v52, v153, v52
	v_cvt_pk_bf16_f32 v48, v52, v48
	v_cvt_pk_bf16_f32 v49, v49, v50
	v_cvt_pk_bf16_f32 v50, v56, v53
	v_cvt_pk_bf16_f32 v51, v54, v51
	global_store_dwordx4 v[64:65], v[48:51], off offset:256
	v_add_co_u32_e32 v56, vcc, s55, v142
	v_pk_add_f32 v[42:43], v[42:43], v[228:229]
	v_pk_add_f32 v[40:41], v[40:41], v[226:227]
	v_pk_add_f32 v[46:47], v[46:47], v[232:233]
	v_pk_add_f32 v[44:45], v[44:45], v[230:231]
	v_mul_f32_e32 v40, 0xbfb8aa3b, v40
	v_mul_f32_e32 v41, 0xbfb8aa3b, v41
	v_mul_f32_e32 v42, 0xbfb8aa3b, v42
	v_mul_f32_e32 v43, 0xbfb8aa3b, v43
	v_mul_f32_e32 v44, 0xbfb8aa3b, v44
	v_mul_f32_e32 v45, 0xbfb8aa3b, v45
	v_mul_f32_e32 v46, 0xbfb8aa3b, v46
	v_mul_f32_e32 v47, 0xbfb8aa3b, v47
	v_exp_f32_e32 v40, v40
	v_exp_f32_e32 v41, v41
	v_exp_f32_e32 v42, v42
	v_exp_f32_e32 v43, v43
	v_exp_f32_e32 v44, v44
	v_exp_f32_e32 v45, v45
	v_exp_f32_e32 v46, v46
	v_exp_f32_e32 v47, v47
	v_add_f32_e32 v40, 1.0, v40
	v_add_f32_e32 v41, 1.0, v41
	v_add_f32_e32 v42, 1.0, v42
	v_add_f32_e32 v43, 1.0, v43
	v_add_f32_e32 v44, 1.0, v44
	v_add_f32_e32 v45, 1.0, v45
	v_add_f32_e32 v46, 1.0, v46
	v_add_f32_e32 v47, 1.0, v47
	v_rcp_f32_e32 v40, v40
	v_rcp_f32_e32 v41, v41
	v_rcp_f32_e32 v42, v42
	v_rcp_f32_e32 v43, v43
	v_rcp_f32_e32 v44, v44
	v_rcp_f32_e32 v45, v45
	v_rcp_f32_e32 v46, v46
	v_rcp_f32_e32 v47, v47
	v_addc_co_u32_e32 v57, vcc, 0, v143, vcc
	v_mul_f32_e32 v40, v153, v40
	v_mul_f32_e32 v41, v153, v41
	v_mul_f32_e32 v42, v153, v42
	v_mul_f32_e32 v43, v153, v43
	v_mul_f32_e32 v44, v153, v44
	v_mul_f32_e32 v45, v153, v45
	v_mul_f32_e32 v46, v153, v46
	v_mul_f32_e32 v47, v153, v47
	v_cvt_pk_bf16_f32 v40, v40, v41
	v_cvt_pk_bf16_f32 v41, v42, v43
	v_cvt_pk_bf16_f32 v42, v44, v45
	v_cvt_pk_bf16_f32 v43, v46, v47
	global_store_dwordx4 v[56:57], v[40:43], off
	v_lshl_add_u64 v[48:49], v[142:143], 0, s[22:23]
	v_pk_add_f32 v[38:39], v[38:39], v[236:237]
	v_pk_add_f32 v[36:37], v[36:37], v[234:235]
	v_pk_add_f32 v[34:35], v[34:35], v[240:241]
	v_pk_add_f32 v[32:33], v[32:33], v[238:239]
	v_mul_f32_e32 v37, 0xbfb8aa3b, v37
	v_mul_f32_e32 v32, 0xbfb8aa3b, v32
	v_mul_f32_e32 v33, 0xbfb8aa3b, v33
	v_mul_f32_e32 v38, 0xbfb8aa3b, v38
	v_mul_f32_e32 v34, 0xbfb8aa3b, v34
	v_mul_f32_e32 v39, 0xbfb8aa3b, v39
	v_mul_f32_e32 v35, 0xbfb8aa3b, v35
	v_mul_f32_e32 v36, 0xbfb8aa3b, v36
	v_exp_f32_e32 v32, v32
	v_exp_f32_e32 v37, v37
	v_exp_f32_e32 v33, v33
	v_exp_f32_e32 v38, v38
	v_exp_f32_e32 v34, v34
	v_exp_f32_e32 v39, v39
	v_exp_f32_e32 v35, v35
	v_exp_f32_e32 v36, v36
	v_add_f32_e32 v32, 1.0, v32
	v_add_f32_e32 v37, 1.0, v37
	v_add_f32_e32 v33, 1.0, v33
	v_add_f32_e32 v38, 1.0, v38
	v_add_f32_e32 v34, 1.0, v34
	v_add_f32_e32 v39, 1.0, v39
	v_add_f32_e32 v35, 1.0, v35
	v_add_f32_e32 v36, 1.0, v36
	v_rcp_f32_e32 v32, v32
	v_rcp_f32_e32 v37, v37
	v_rcp_f32_e32 v33, v33
	v_rcp_f32_e32 v38, v38
	v_rcp_f32_e32 v34, v34
	v_rcp_f32_e32 v39, v39
	v_rcp_f32_e32 v35, v35
	v_rcp_f32_e32 v36, v36
	v_mul_f32_e32 v40, v153, v32
	v_mul_f32_e32 v32, v153, v37
	v_mul_f32_e32 v37, v153, v33
	v_mul_f32_e32 v33, v153, v38
	v_mul_f32_e32 v38, v153, v34
	v_mul_f32_e32 v34, v153, v39
	v_mul_f32_e32 v35, v153, v35
	v_mul_f32_e32 v36, v153, v36
	v_cvt_pk_bf16_f32 v32, v36, v32
	v_cvt_pk_bf16_f32 v33, v33, v34
	v_cvt_pk_bf16_f32 v34, v40, v37
	v_cvt_pk_bf16_f32 v35, v38, v35
	global_store_dwordx4 v[48:49], v[32:35], off offset:256
	v_add_co_u32_e32 v40, vcc, s56, v142
	v_pk_add_f32 v[26:27], v[26:27], v[228:229]
	v_pk_add_f32 v[24:25], v[24:25], v[226:227]
	v_pk_add_f32 v[30:31], v[30:31], v[232:233]
	v_pk_add_f32 v[28:29], v[28:29], v[230:231]
	v_mul_f32_e32 v24, 0xbfb8aa3b, v24
	v_mul_f32_e32 v25, 0xbfb8aa3b, v25
	v_mul_f32_e32 v26, 0xbfb8aa3b, v26
	v_mul_f32_e32 v27, 0xbfb8aa3b, v27
	v_mul_f32_e32 v28, 0xbfb8aa3b, v28
	v_mul_f32_e32 v29, 0xbfb8aa3b, v29
	v_mul_f32_e32 v30, 0xbfb8aa3b, v30
	v_mul_f32_e32 v31, 0xbfb8aa3b, v31
	v_exp_f32_e32 v24, v24
	v_exp_f32_e32 v25, v25
	v_exp_f32_e32 v26, v26
	v_exp_f32_e32 v27, v27
	v_exp_f32_e32 v28, v28
	v_exp_f32_e32 v29, v29
	v_exp_f32_e32 v30, v30
	v_exp_f32_e32 v31, v31
	v_add_f32_e32 v24, 1.0, v24
	v_add_f32_e32 v25, 1.0, v25
	v_add_f32_e32 v26, 1.0, v26
	v_add_f32_e32 v27, 1.0, v27
	v_add_f32_e32 v28, 1.0, v28
	v_add_f32_e32 v29, 1.0, v29
	v_add_f32_e32 v30, 1.0, v30
	v_add_f32_e32 v31, 1.0, v31
	v_rcp_f32_e32 v24, v24
	v_rcp_f32_e32 v25, v25
	v_rcp_f32_e32 v26, v26
	v_rcp_f32_e32 v27, v27
	v_rcp_f32_e32 v28, v28
	v_rcp_f32_e32 v29, v29
	v_rcp_f32_e32 v30, v30
	v_rcp_f32_e32 v31, v31
	v_addc_co_u32_e32 v41, vcc, 0, v143, vcc
	v_mul_f32_e32 v24, v153, v24
	v_mul_f32_e32 v25, v153, v25
	v_mul_f32_e32 v26, v153, v26
	v_mul_f32_e32 v27, v153, v27
	v_mul_f32_e32 v28, v153, v28
	v_mul_f32_e32 v29, v153, v29
	v_mul_f32_e32 v30, v153, v30
	v_mul_f32_e32 v31, v153, v31
	v_cvt_pk_bf16_f32 v24, v24, v25
	v_cvt_pk_bf16_f32 v25, v26, v27
	v_cvt_pk_bf16_f32 v26, v28, v29
	v_cvt_pk_bf16_f32 v27, v30, v31
	global_store_dwordx4 v[40:41], v[24:27], off
	v_lshl_add_u64 v[32:33], v[142:143], 0, s[24:25]
	v_pk_add_f32 v[22:23], v[22:23], v[236:237]
	v_pk_add_f32 v[20:21], v[20:21], v[234:235]
	v_pk_add_f32 v[18:19], v[18:19], v[240:241]
	v_pk_add_f32 v[16:17], v[16:17], v[238:239]
	v_mul_f32_e32 v21, 0xbfb8aa3b, v21
	v_mul_f32_e32 v16, 0xbfb8aa3b, v16
	v_mul_f32_e32 v17, 0xbfb8aa3b, v17
	v_mul_f32_e32 v22, 0xbfb8aa3b, v22
	v_mul_f32_e32 v18, 0xbfb8aa3b, v18
	v_mul_f32_e32 v23, 0xbfb8aa3b, v23
	v_mul_f32_e32 v19, 0xbfb8aa3b, v19
	v_mul_f32_e32 v20, 0xbfb8aa3b, v20
	v_exp_f32_e32 v16, v16
	v_exp_f32_e32 v21, v21
	v_exp_f32_e32 v17, v17
	v_exp_f32_e32 v22, v22
	v_exp_f32_e32 v18, v18
	v_exp_f32_e32 v23, v23
	v_exp_f32_e32 v19, v19
	v_exp_f32_e32 v20, v20
	v_add_f32_e32 v16, 1.0, v16
	v_add_f32_e32 v21, 1.0, v21
	v_add_f32_e32 v17, 1.0, v17
	v_add_f32_e32 v22, 1.0, v22
	v_add_f32_e32 v18, 1.0, v18
	v_add_f32_e32 v23, 1.0, v23
	v_add_f32_e32 v19, 1.0, v19
	v_add_f32_e32 v20, 1.0, v20
	v_rcp_f32_e32 v16, v16
	v_rcp_f32_e32 v21, v21
	v_rcp_f32_e32 v17, v17
	v_rcp_f32_e32 v22, v22
	v_rcp_f32_e32 v18, v18
	v_rcp_f32_e32 v23, v23
	v_rcp_f32_e32 v19, v19
	v_rcp_f32_e32 v20, v20
	v_mul_f32_e32 v24, v153, v16
	v_mul_f32_e32 v16, v153, v21
	v_mul_f32_e32 v21, v153, v17
	v_mul_f32_e32 v17, v153, v22
	v_mul_f32_e32 v22, v153, v18
	v_mul_f32_e32 v18, v153, v23
	v_mul_f32_e32 v19, v153, v19
	v_mul_f32_e32 v20, v153, v20
	v_cvt_pk_bf16_f32 v16, v20, v16
	v_cvt_pk_bf16_f32 v17, v17, v18
	v_cvt_pk_bf16_f32 v18, v24, v21
	v_cvt_pk_bf16_f32 v19, v22, v19
	global_store_dwordx4 v[32:33], v[16:19], off offset:256
	v_add_co_u32_e32 v24, vcc, s57, v142
	v_pk_add_f32 v[10:11], v[10:11], v[228:229]
	v_pk_add_f32 v[8:9], v[8:9], v[226:227]
	v_pk_add_f32 v[14:15], v[14:15], v[232:233]
	v_pk_add_f32 v[12:13], v[12:13], v[230:231]
	v_mul_f32_e32 v8, 0xbfb8aa3b, v8
	v_mul_f32_e32 v9, 0xbfb8aa3b, v9
	v_mul_f32_e32 v10, 0xbfb8aa3b, v10
	v_mul_f32_e32 v11, 0xbfb8aa3b, v11
	v_mul_f32_e32 v12, 0xbfb8aa3b, v12
	v_mul_f32_e32 v13, 0xbfb8aa3b, v13
	v_mul_f32_e32 v14, 0xbfb8aa3b, v14
	v_mul_f32_e32 v15, 0xbfb8aa3b, v15
	v_exp_f32_e32 v8, v8
	v_exp_f32_e32 v9, v9
	v_exp_f32_e32 v10, v10
	v_exp_f32_e32 v11, v11
	v_exp_f32_e32 v12, v12
	v_exp_f32_e32 v13, v13
	v_exp_f32_e32 v14, v14
	v_exp_f32_e32 v15, v15
	v_add_f32_e32 v8, 1.0, v8
	v_add_f32_e32 v9, 1.0, v9
	v_add_f32_e32 v10, 1.0, v10
	v_add_f32_e32 v11, 1.0, v11
	v_add_f32_e32 v12, 1.0, v12
	v_add_f32_e32 v13, 1.0, v13
	v_add_f32_e32 v14, 1.0, v14
	v_add_f32_e32 v15, 1.0, v15
	v_rcp_f32_e32 v8, v8
	v_rcp_f32_e32 v9, v9
	v_rcp_f32_e32 v10, v10
	v_rcp_f32_e32 v11, v11
	v_rcp_f32_e32 v12, v12
	v_rcp_f32_e32 v13, v13
	v_rcp_f32_e32 v14, v14
	v_rcp_f32_e32 v15, v15
	v_addc_co_u32_e32 v25, vcc, 0, v143, vcc
	v_mul_f32_e32 v8, v153, v8
	v_mul_f32_e32 v9, v153, v9
	v_mul_f32_e32 v10, v153, v10
	v_mul_f32_e32 v11, v153, v11
	v_mul_f32_e32 v12, v153, v12
	v_mul_f32_e32 v13, v153, v13
	v_mul_f32_e32 v14, v153, v14
	v_mul_f32_e32 v15, v153, v15
	v_cvt_pk_bf16_f32 v8, v8, v9
	v_cvt_pk_bf16_f32 v9, v10, v11
	v_cvt_pk_bf16_f32 v10, v12, v13
	v_cvt_pk_bf16_f32 v11, v14, v15
	global_store_dwordx4 v[24:25], v[8:11], off
	v_lshl_add_u64 v[16:17], v[142:143], 0, s[26:27]
	s_and_b64 vcc, exec, s[2:3]
	s_mov_b64 s[2:3], -1
	v_pk_add_f32 v[6:7], v[6:7], v[236:237]
	v_pk_add_f32 v[4:5], v[4:5], v[234:235]
	v_pk_add_f32 v[2:3], v[2:3], v[240:241]
	v_pk_add_f32 v[0:1], v[0:1], v[238:239]
	v_mul_f32_e32 v5, 0xbfb8aa3b, v5
	v_mul_f32_e32 v0, 0xbfb8aa3b, v0
	v_mul_f32_e32 v1, 0xbfb8aa3b, v1
	v_mul_f32_e32 v6, 0xbfb8aa3b, v6
	v_mul_f32_e32 v2, 0xbfb8aa3b, v2
	v_mul_f32_e32 v7, 0xbfb8aa3b, v7
	v_mul_f32_e32 v3, 0xbfb8aa3b, v3
	v_mul_f32_e32 v4, 0xbfb8aa3b, v4
	v_exp_f32_e32 v0, v0
	v_exp_f32_e32 v5, v5
	v_exp_f32_e32 v1, v1
	v_exp_f32_e32 v6, v6
	v_exp_f32_e32 v2, v2
	v_exp_f32_e32 v7, v7
	v_exp_f32_e32 v3, v3
	v_exp_f32_e32 v4, v4
	v_add_f32_e32 v0, 1.0, v0
	v_add_f32_e32 v5, 1.0, v5
	v_add_f32_e32 v1, 1.0, v1
	v_add_f32_e32 v6, 1.0, v6
	v_add_f32_e32 v2, 1.0, v2
	v_add_f32_e32 v7, 1.0, v7
	v_add_f32_e32 v3, 1.0, v3
	v_add_f32_e32 v4, 1.0, v4
	v_rcp_f32_e32 v0, v0
	v_rcp_f32_e32 v5, v5
	v_rcp_f32_e32 v1, v1
	v_rcp_f32_e32 v6, v6
	v_rcp_f32_e32 v2, v2
	v_rcp_f32_e32 v7, v7
	v_rcp_f32_e32 v3, v3
	v_rcp_f32_e32 v4, v4
	v_mul_f32_e32 v8, v153, v0
	v_mul_f32_e32 v0, v153, v5
	v_mul_f32_e32 v5, v153, v1
	v_mul_f32_e32 v1, v153, v6
	v_mul_f32_e32 v6, v153, v2
	v_mul_f32_e32 v2, v153, v7
	v_mul_f32_e32 v3, v153, v3
	v_mul_f32_e32 v4, v153, v4
	v_cvt_pk_bf16_f32 v0, v4, v0
	v_cvt_pk_bf16_f32 v1, v1, v2
	v_cvt_pk_bf16_f32 v2, v8, v5
	v_cvt_pk_bf16_f32 v3, v6, v3
	global_store_dwordx4 v[16:17], v[0:3], off offset:256
	s_cbranch_vccnz .LBB0_394
	s_andn2_b64 vcc, exec, s[6:7]
	s_cbranch_vccnz .LBB0_393
	s_barrier
	s_branch .LBB0_393
